# DSA index-score loop rewritten: 8 independent MFMA accumulators per key tile, key fragments reloaded in place (no copy buffer)
# speedup vs baseline: 1.1830x; 1.1830x over previous
.LBB0_1628:
	s_and_b32 s6, s53, 0xf8
	s_and_b32 s7, s53, 0x100
	s_xor_b32 s8, s6, 0xf8
	s_cmp_eq_u32 s7, 0
	v_mov_b32_e32 v0, 2.0
	v_mov_b32_e32 v2, 1.0
	s_cselect_b32 s6, s6, s8
	s_and_b32 s7, s53, 0xffffff00
	v_permlane16_swap_b32_e32 v2, v0
	s_or_b32 s54, s6, s7
	v_add_f32_e32 v2, v2, v0
	v_mov_b32_e32 v0, 4.0
	v_mov_b32_e32 v3, 0x41000000
	s_lshl_b32 s7, s53, 12
	s_add_i32 s8, s54, 23
	v_permlane16_swap_b32_e32 v0, v3
	s_ashr_i32 s6, s8, 4
	s_and_b32 s16, s7, 0x7000
	v_add_f32_e32 v3, v0, v3
	s_cmp_ge_i32 s14, s6
	s_nop 0
	v_permlane32_swap_b32_e32 v2, v3
	s_cbranch_scc1 .LBB0_1639
	s_lshl_b32 s7, s49, 7
	s_and_b32 s7, s7, 0x380000
	v_or_b32_e32 v0, s7, v189
	v_lshl_add_u64 v[180:181], v[178:179], 0, v[0:1]
	v_add_f32_e32 v0, v2, v3
	v_cvt_i32_f32_e32 v0, v0
	s_add_i32 s7, s6, -1
	s_min_i32 s10, s44, s7
	s_ashr_i32 s11, s10, 31
	v_ffbl_b32_e32 v2, v0
	v_cmp_ne_u32_e32 vcc, 0, v0
	v_or_b32_e32 v0, s16, v187
	v_lshlrev_b32_e32 v0, 7, v0
	v_lshl_add_u64 v[182:183], v[164:165], 0, v[0:1]
	s_lshl_b64 s[10:11], s[10:11], 11
	v_lshl_add_u64 v[232:233], v[182:183], 0, s[10:11]
	s_min_i32 s10, s45, s7
	s_ashr_i32 s11, s10, 31
	v_add_u32_e32 v2, 1, v2
	s_lshl_b64 s[10:11], s[10:11], 11
	v_cndmask_b32_e32 v116, 0, v2, vcc
	v_lshl_add_u64 v[230:231], v[182:183], 0, s[10:11]
	s_min_i32 s10, s46, s7
	v_add_u32_e32 v2, s54, v116
	s_ashr_i32 s11, s10, 31
	v_add_u32_e32 v0, -3, v2
	v_add_u32_e32 v223, 1, v2
	v_add_u32_e32 v2, 0, v162
	s_lshl_b64 s[10:11], s[10:11], 11
	v_add_u32_e32 v86, 0x26a00, v2
	v_lshl_add_u64 v[228:229], v[182:183], 0, s[10:11]
	ds_read_b128 v[2:5], v86 offset:448
	ds_read_b128 v[6:9], v217 offset:14400
	ds_read_b128 v[10:13], v217 offset:14336
	ds_read_b128 v[14:17], v86 offset:384
	ds_read_b128 v[18:21], v217 offset:12352
	ds_read_b128 v[22:25], v217 offset:12288
	ds_read_b128 v[26:29], v86 offset:320
	ds_read_b128 v[30:33], v217 offset:10304
	ds_read_b128 v[34:37], v217 offset:10240
	ds_read_b128 v[38:41], v86 offset:256
	ds_read_b128 v[42:45], v217 offset:8256
	ds_read_b128 v[46:49], v217 offset:8192
	ds_read_b128 v[50:53], v86 offset:192
	ds_read_b128 v[54:57], v217 offset:6208
	ds_read_b128 v[58:61], v217 offset:6144
	ds_read_b128 v[62:65], v86 offset:128
	ds_read_b128 v[66:69], v217 offset:4160
	ds_read_b128 v[70:73], v217 offset:4096
	ds_read_b128 v[74:77], v86 offset:64
	ds_read_b128 v[78:81], v217 offset:2112
	ds_read_b128 v[82:85], v217 offset:2048
	ds_read_b128 v[86:89], v86
	ds_read_b128 v[90:93], v217 offset:64
	ds_read_b128 v[94:97], v217
	v_lshl_add_u64 v[226:227], v[182:183], 0, s[30:31]
	global_load_dwordx4 v[158:161], v[226:227], off
	global_load_dwordx4 v[154:157], v[226:227], off offset:64
	global_load_dwordx4 v[150:153], v[228:229], off
	global_load_dwordx4 v[146:149], v[228:229], off offset:64
	global_load_dwordx4 v[110:113], v[230:231], off
	global_load_dwordx4 v[106:109], v[230:231], off offset:64
	global_load_dwordx4 v[102:105], v[232:233], off
	global_load_dwordx4 v[98:101], v[232:233], off offset:64
	s_waitcnt lgkmcnt(0)
	v_mov_b32_e32 v184, v87
	v_mov_b32_e32 v87, v89
	v_mov_b32_e32 v89, v76
	v_mov_b32_e32 v76, v63
	v_mov_b32_e32 v63, v65
	v_mov_b32_e32 v65, v52
	v_mov_b32_e32 v52, v39
	v_mov_b32_e32 v39, v41
	v_mov_b32_e32 v41, v28
	v_mov_b32_e32 v28, v15
	v_mov_b32_e32 v15, v17
	v_mov_b32_e32 v17, v4
	v_lshl_add_u32 v4, v116, 14, v215
	v_mov_b32_e32 v185, v88
	v_mov_b32_e32 v88, v75
	v_mov_b32_e32 v75, v77
	v_mov_b32_e32 v77, v64
	v_mov_b32_e32 v64, v51
	v_mov_b32_e32 v51, v53
	v_mov_b32_e32 v53, v40
	v_mov_b32_e32 v40, v27
	v_mov_b32_e32 v27, v29
	v_mov_b32_e32 v29, v16
	v_mov_b32_e32 v16, v3
	v_mov_b32_e32 v3, v5
	v_mov_b32_e32 v5, v216
	s_mov_b32 s9, s15
.Lsc_step:
	s_sub_i32 s10, s9, 24
	s_waitcnt vmcnt(6)
	v_mfma_f32_16x16x32_bf16 v[114:117], v[94:97], v[158:161], 0
	v_mfma_f32_16x16x32_bf16 v[118:121], v[82:85], v[158:161], 0
	v_mfma_f32_16x16x32_bf16 v[122:125], v[70:73], v[158:161], 0
	v_mfma_f32_16x16x32_bf16 v[126:129], v[58:61], v[158:161], 0
	v_mfma_f32_16x16x32_bf16 v[130:133], v[46:49], v[158:161], 0
	v_mfma_f32_16x16x32_bf16 v[134:137], v[34:37], v[158:161], 0
	v_mfma_f32_16x16x32_bf16 v[138:141], v[22:25], v[158:161], 0
	v_mfma_f32_16x16x32_bf16 v[142:145], v[10:13], v[158:161], 0
	v_mfma_f32_16x16x32_bf16 v[114:117], v[90:93], v[154:157], v[114:117]
	v_mfma_f32_16x16x32_bf16 v[118:121], v[78:81], v[154:157], v[118:121]
	v_mfma_f32_16x16x32_bf16 v[122:125], v[66:69], v[154:157], v[122:125]
	v_mfma_f32_16x16x32_bf16 v[126:129], v[54:57], v[154:157], v[126:129]
	v_mfma_f32_16x16x32_bf16 v[130:133], v[42:45], v[154:157], v[130:133]
	v_mfma_f32_16x16x32_bf16 v[134:137], v[30:33], v[154:157], v[134:137]
	v_mfma_f32_16x16x32_bf16 v[138:141], v[18:21], v[154:157], v[138:141]
	v_mfma_f32_16x16x32_bf16 v[142:145], v[6:9], v[154:157], v[142:145]
	s_cmp_lt_i32 s10, s6
	s_cbranch_scc0 .Lsc_np0
	global_load_dwordx4 v[158:161], v[180:181], off
	global_load_dwordx4 v[154:157], v[180:181], off offset:64
.Lsc_np0:
	v_add_u32_e32 v234, 0xfffffe80, v5
	v_cmp_le_i32_e64 s[90:91], v234, v0
	v_cmp_le_i32_e64 s[92:93], v234, v223
	v_add_u32_e32 v237, 0x10000, v4
	s_nop 1
	v_max_i32_e32 v226, 0, v115
	v_max_i32_e32 v228, 0, v119
	v_max_i32_e32 v227, 0, v116
	v_max_i32_e32 v229, 0, v120
	v_max_i32_e32 v115, 0, v117
	v_max_i32_e32 v119, 0, v121
	v_max_i32_e32 v114, 0, v114
	v_max_i32_e32 v118, 0, v118
	v_pk_mul_f32 v[114:115], v[86:87], v[114:115]
	v_pk_mul_f32 v[118:119], v[74:75], v[118:119]
	v_pk_fma_f32 v[226:227], v[184:185], v[226:227], v[114:115]
	v_pk_fma_f32 v[228:229], v[88:89], v[228:229], v[118:119]
	v_add_f32_e32 v116, v226, v227
	v_add_f32_e32 v120, v228, v229
	v_max_i32_e32 v226, 0, v123
	v_max_i32_e32 v228, 0, v127
	v_max_i32_e32 v227, 0, v124
	v_max_i32_e32 v229, 0, v128
	v_max_i32_e32 v123, 0, v125
	v_max_i32_e32 v127, 0, v129
	v_max_i32_e32 v122, 0, v122
	v_max_i32_e32 v126, 0, v126
	v_pk_mul_f32 v[122:123], v[62:63], v[122:123]
	v_pk_mul_f32 v[126:127], v[50:51], v[126:127]
	v_pk_fma_f32 v[226:227], v[76:77], v[226:227], v[122:123]
	v_pk_fma_f32 v[228:229], v[64:65], v[228:229], v[126:127]
	v_add_f32_e32 v124, v226, v227
	v_add_f32_e32 v128, v228, v229
	v_max_i32_e32 v226, 0, v131
	v_max_i32_e32 v228, 0, v135
	v_max_i32_e32 v227, 0, v132
	v_max_i32_e32 v229, 0, v136
	v_max_i32_e32 v131, 0, v133
	v_max_i32_e32 v135, 0, v137
	v_max_i32_e32 v130, 0, v130
	v_max_i32_e32 v134, 0, v134
	v_pk_mul_f32 v[130:131], v[38:39], v[130:131]
	v_pk_mul_f32 v[134:135], v[26:27], v[134:135]
	v_pk_fma_f32 v[226:227], v[52:53], v[226:227], v[130:131]
	v_pk_fma_f32 v[228:229], v[40:41], v[228:229], v[134:135]
	v_add_f32_e32 v132, v226, v227
	v_add_f32_e32 v136, v228, v229
	v_max_i32_e32 v226, 0, v139
	v_max_i32_e32 v228, 0, v143
	v_max_i32_e32 v227, 0, v140
	v_max_i32_e32 v229, 0, v144
	v_max_i32_e32 v139, 0, v141
	v_max_i32_e32 v143, 0, v145
	v_max_i32_e32 v138, 0, v138
	v_max_i32_e32 v142, 0, v142
	v_pk_mul_f32 v[138:139], v[14:15], v[138:139]
	v_pk_mul_f32 v[142:143], v[2:3], v[142:143]
	v_pk_fma_f32 v[226:227], v[28:29], v[226:227], v[138:139]
	v_pk_fma_f32 v[228:229], v[16:17], v[228:229], v[142:143]
	v_add_f32_e32 v140, v226, v227
	v_add_f32_e32 v144, v228, v229
	s_nop 1
	v_permlane16_swap_b32_e32 v116, v120
	v_permlane16_swap_b32_e32 v124, v128
	v_permlane16_swap_b32_e32 v132, v136
	v_permlane16_swap_b32_e32 v140, v144
	v_add_f32_e32 v233, v116, v120
	v_add_f32_e32 v231, v124, v128
	v_add_f32_e32 v232, v132, v136
	v_add_f32_e32 v230, v140, v144
	s_nop 1
	v_permlane32_swap_b32_e32 v233, v231
	v_permlane32_swap_b32_e32 v232, v230
	v_pk_add_f32 v[230:231], v[232:233], v[230:231]
	v_pk_add_f32 v[230:231], v[230:231], 0 op_sel_hi:[1,0]
	v_ashrrev_i32_e32 v235, 31, v231
	v_ashrrev_i32_e32 v236, 31, v230
	v_or_b32_e32 v235, 0x80000000, v235
	v_or_b32_e32 v236, 0x80000000, v236
	v_xor_b32_e32 v235, v231, v235
	v_xor_b32_e32 v236, v230, v236
	v_cndmask_b32_e64 v235, 0, v235, s[90:91]
	v_cndmask_b32_e64 v236, 0, v236, s[92:93]
	ds_write_b32 v4, v235
	ds_write_b32 v237, v236
	s_sub_i32 s11, s9, 48
	s_cmp_ge_i32 s11, s6
	s_cbranch_scc1 .Lsc_exit
	s_cmp_lt_i32 s10, s6
	s_cbranch_scc1 .Lsc_w1n
	s_waitcnt vmcnt(4)
	s_branch .Lsc_m1
.Lsc_w1n:
	s_waitcnt vmcnt(6)
.Lsc_m1:
	v_mfma_f32_16x16x32_bf16 v[114:117], v[94:97], v[150:153], 0
	v_mfma_f32_16x16x32_bf16 v[118:121], v[82:85], v[150:153], 0
	v_mfma_f32_16x16x32_bf16 v[122:125], v[70:73], v[150:153], 0
	v_mfma_f32_16x16x32_bf16 v[126:129], v[58:61], v[150:153], 0
	v_mfma_f32_16x16x32_bf16 v[130:133], v[46:49], v[150:153], 0
	v_mfma_f32_16x16x32_bf16 v[134:137], v[34:37], v[150:153], 0
	v_mfma_f32_16x16x32_bf16 v[138:141], v[22:25], v[150:153], 0
	v_mfma_f32_16x16x32_bf16 v[142:145], v[10:13], v[150:153], 0
	v_mfma_f32_16x16x32_bf16 v[114:117], v[90:93], v[146:149], v[114:117]
	v_mfma_f32_16x16x32_bf16 v[118:121], v[78:81], v[146:149], v[118:121]
	v_mfma_f32_16x16x32_bf16 v[122:125], v[66:69], v[146:149], v[122:125]
	v_mfma_f32_16x16x32_bf16 v[126:129], v[54:57], v[146:149], v[126:129]
	v_mfma_f32_16x16x32_bf16 v[130:133], v[42:45], v[146:149], v[130:133]
	v_mfma_f32_16x16x32_bf16 v[134:137], v[30:33], v[146:149], v[134:137]
	v_mfma_f32_16x16x32_bf16 v[138:141], v[18:21], v[146:149], v[138:141]
	v_mfma_f32_16x16x32_bf16 v[142:145], v[6:9], v[146:149], v[142:145]
	s_cmp_lt_i32 s10, s6
	s_cbranch_scc0 .Lsc_np1
	s_add_i32 s11, s9, -16
	s_min_i32 s12, s11, s7
	s_ashr_i32 s13, s12, 31
	s_lshl_b64 s[12:13], s[12:13], 11
	v_lshl_add_u64 v[244:245], v[182:183], 0, s[12:13]
	global_load_dwordx4 v[150:153], v[244:245], off
	global_load_dwordx4 v[146:149], v[244:245], off offset:64
.Lsc_np1:
	v_add_u32_e32 v234, 0xffffff00, v5
	v_cmp_le_i32_e64 s[90:91], v234, v0
	v_cmp_le_i32_e64 s[92:93], v234, v223
	v_add_u32_e32 v237, 0x10200, v4
	s_nop 1
	v_max_i32_e32 v226, 0, v115
	v_max_i32_e32 v228, 0, v119
	v_max_i32_e32 v227, 0, v116
	v_max_i32_e32 v229, 0, v120
	v_max_i32_e32 v115, 0, v117
	v_max_i32_e32 v119, 0, v121
	v_max_i32_e32 v114, 0, v114
	v_max_i32_e32 v118, 0, v118
	v_pk_mul_f32 v[114:115], v[86:87], v[114:115]
	v_pk_mul_f32 v[118:119], v[74:75], v[118:119]
	v_pk_fma_f32 v[226:227], v[184:185], v[226:227], v[114:115]
	v_pk_fma_f32 v[228:229], v[88:89], v[228:229], v[118:119]
	v_add_f32_e32 v116, v226, v227
	v_add_f32_e32 v120, v228, v229
	v_max_i32_e32 v226, 0, v123
	v_max_i32_e32 v228, 0, v127
	v_max_i32_e32 v227, 0, v124
	v_max_i32_e32 v229, 0, v128
	v_max_i32_e32 v123, 0, v125
	v_max_i32_e32 v127, 0, v129
	v_max_i32_e32 v122, 0, v122
	v_max_i32_e32 v126, 0, v126
	v_pk_mul_f32 v[122:123], v[62:63], v[122:123]
	v_pk_mul_f32 v[126:127], v[50:51], v[126:127]
	v_pk_fma_f32 v[226:227], v[76:77], v[226:227], v[122:123]
	v_pk_fma_f32 v[228:229], v[64:65], v[228:229], v[126:127]
	v_add_f32_e32 v124, v226, v227
	v_add_f32_e32 v128, v228, v229
	v_max_i32_e32 v226, 0, v131
	v_max_i32_e32 v228, 0, v135
	v_max_i32_e32 v227, 0, v132
	v_max_i32_e32 v229, 0, v136
	v_max_i32_e32 v131, 0, v133
	v_max_i32_e32 v135, 0, v137
	v_max_i32_e32 v130, 0, v130
	v_max_i32_e32 v134, 0, v134
	v_pk_mul_f32 v[130:131], v[38:39], v[130:131]
	v_pk_mul_f32 v[134:135], v[26:27], v[134:135]
	v_pk_fma_f32 v[226:227], v[52:53], v[226:227], v[130:131]
	v_pk_fma_f32 v[228:229], v[40:41], v[228:229], v[134:135]
	v_add_f32_e32 v132, v226, v227
	v_add_f32_e32 v136, v228, v229
	v_max_i32_e32 v226, 0, v139
	v_max_i32_e32 v228, 0, v143
	v_max_i32_e32 v227, 0, v140
	v_max_i32_e32 v229, 0, v144
	v_max_i32_e32 v139, 0, v141
	v_max_i32_e32 v143, 0, v145
	v_max_i32_e32 v138, 0, v138
	v_max_i32_e32 v142, 0, v142
	v_pk_mul_f32 v[138:139], v[14:15], v[138:139]
	v_pk_mul_f32 v[142:143], v[2:3], v[142:143]
	v_pk_fma_f32 v[226:227], v[28:29], v[226:227], v[138:139]
	v_pk_fma_f32 v[228:229], v[16:17], v[228:229], v[142:143]
	v_add_f32_e32 v140, v226, v227
	v_add_f32_e32 v144, v228, v229
	s_nop 1
	v_permlane16_swap_b32_e32 v116, v120
	v_permlane16_swap_b32_e32 v124, v128
	v_permlane16_swap_b32_e32 v132, v136
	v_permlane16_swap_b32_e32 v140, v144
	v_add_f32_e32 v233, v116, v120
	v_add_f32_e32 v231, v124, v128
	v_add_f32_e32 v232, v132, v136
	v_add_f32_e32 v230, v140, v144
	s_nop 1
	v_permlane32_swap_b32_e32 v233, v231
	v_permlane32_swap_b32_e32 v232, v230
	v_pk_add_f32 v[230:231], v[232:233], v[230:231]
	v_pk_add_f32 v[230:231], v[230:231], 0 op_sel_hi:[1,0]
	v_ashrrev_i32_e32 v235, 31, v231
	v_ashrrev_i32_e32 v236, 31, v230
	v_or_b32_e32 v235, 0x80000000, v235
	v_or_b32_e32 v236, 0x80000000, v236
	v_xor_b32_e32 v235, v231, v235
	v_xor_b32_e32 v236, v230, v236
	v_cndmask_b32_e64 v235, 0, v235, s[90:91]
	v_cndmask_b32_e64 v236, 0, v236, s[92:93]
	ds_write_b32 v4, v235 offset:512
	ds_write_b32 v237, v236
	s_sub_i32 s11, s9, 40
	s_cmp_ge_i32 s11, s6
	s_cbranch_scc1 .Lsc_exit
	s_cmp_lt_i32 s10, s6
	s_cbranch_scc1 .Lsc_w2n
	s_waitcnt vmcnt(2)
	s_branch .Lsc_m2

.Lsc_m2:
	v_mfma_f32_16x16x32_bf16 v[114:117], v[94:97], v[110:113], 0
	v_mfma_f32_16x16x32_bf16 v[118:121], v[82:85], v[110:113], 0
	v_mfma_f32_16x16x32_bf16 v[122:125], v[70:73], v[110:113], 0
	v_mfma_f32_16x16x32_bf16 v[126:129], v[58:61], v[110:113], 0
	v_mfma_f32_16x16x32_bf16 v[130:133], v[46:49], v[110:113], 0
	v_mfma_f32_16x16x32_bf16 v[134:137], v[34:37], v[110:113], 0
	v_mfma_f32_16x16x32_bf16 v[138:141], v[22:25], v[110:113], 0
	v_mfma_f32_16x16x32_bf16 v[142:145], v[10:13], v[110:113], 0
	v_mfma_f32_16x16x32_bf16 v[114:117], v[90:93], v[106:109], v[114:117]
	v_mfma_f32_16x16x32_bf16 v[118:121], v[78:81], v[106:109], v[118:121]
	v_mfma_f32_16x16x32_bf16 v[122:125], v[66:69], v[106:109], v[122:125]
	v_mfma_f32_16x16x32_bf16 v[126:129], v[54:57], v[106:109], v[126:129]
	v_mfma_f32_16x16x32_bf16 v[130:133], v[42:45], v[106:109], v[130:133]
	v_mfma_f32_16x16x32_bf16 v[134:137], v[30:33], v[106:109], v[134:137]
	v_mfma_f32_16x16x32_bf16 v[138:141], v[18:21], v[106:109], v[138:141]
	v_mfma_f32_16x16x32_bf16 v[142:145], v[6:9], v[106:109], v[142:145]
	s_cmp_lt_i32 s10, s6
	s_cbranch_scc0 .Lsc_np2
	s_add_i32 s11, s9, -8
	s_min_i32 s12, s11, s7
	s_ashr_i32 s13, s12, 31
	s_lshl_b64 s[12:13], s[12:13], 11
	v_lshl_add_u64 v[244:245], v[182:183], 0, s[12:13]
	global_load_dwordx4 v[110:113], v[244:245], off
	global_load_dwordx4 v[106:109], v[244:245], off offset:64
.Lsc_np2:
	v_add_u32_e32 v234, 0xffffff80, v5
	v_cmp_le_i32_e64 s[90:91], v234, v0
	v_cmp_le_i32_e64 s[92:93], v234, v223
	v_add_u32_e32 v237, 0x10400, v4
	s_nop 1
	v_max_i32_e32 v226, 0, v115
	v_max_i32_e32 v228, 0, v119
	v_max_i32_e32 v227, 0, v116
	v_max_i32_e32 v229, 0, v120
	v_max_i32_e32 v115, 0, v117
	v_max_i32_e32 v119, 0, v121
	v_max_i32_e32 v114, 0, v114
	v_max_i32_e32 v118, 0, v118
	v_pk_mul_f32 v[114:115], v[86:87], v[114:115]
	v_pk_mul_f32 v[118:119], v[74:75], v[118:119]
	v_pk_fma_f32 v[226:227], v[184:185], v[226:227], v[114:115]
	v_pk_fma_f32 v[228:229], v[88:89], v[228:229], v[118:119]
	v_add_f32_e32 v116, v226, v227
	v_add_f32_e32 v120, v228, v229
	v_max_i32_e32 v226, 0, v123
	v_max_i32_e32 v228, 0, v127
	v_max_i32_e32 v227, 0, v124
	v_max_i32_e32 v229, 0, v128
	v_max_i32_e32 v123, 0, v125
	v_max_i32_e32 v127, 0, v129
	v_max_i32_e32 v122, 0, v122
	v_max_i32_e32 v126, 0, v126
	v_pk_mul_f32 v[122:123], v[62:63], v[122:123]
	v_pk_mul_f32 v[126:127], v[50:51], v[126:127]
	v_pk_fma_f32 v[226:227], v[76:77], v[226:227], v[122:123]
	v_pk_fma_f32 v[228:229], v[64:65], v[228:229], v[126:127]
	v_add_f32_e32 v124, v226, v227
	v_add_f32_e32 v128, v228, v229
	v_max_i32_e32 v226, 0, v131
	v_max_i32_e32 v228, 0, v135
	v_max_i32_e32 v227, 0, v132
	v_max_i32_e32 v229, 0, v136
	v_max_i32_e32 v131, 0, v133
	v_max_i32_e32 v135, 0, v137
	v_max_i32_e32 v130, 0, v130
	v_max_i32_e32 v134, 0, v134
	v_pk_mul_f32 v[130:131], v[38:39], v[130:131]
	v_pk_mul_f32 v[134:135], v[26:27], v[134:135]
	v_pk_fma_f32 v[226:227], v[52:53], v[226:227], v[130:131]
	v_pk_fma_f32 v[228:229], v[40:41], v[228:229], v[134:135]
	v_add_f32_e32 v132, v226, v227
	v_add_f32_e32 v136, v228, v229
	v_max_i32_e32 v226, 0, v139
	v_max_i32_e32 v228, 0, v143
	v_max_i32_e32 v227, 0, v140
	v_max_i32_e32 v229, 0, v144
	v_max_i32_e32 v139, 0, v141
	v_max_i32_e32 v143, 0, v145
	v_max_i32_e32 v138, 0, v138
	v_max_i32_e32 v142, 0, v142
	v_pk_mul_f32 v[138:139], v[14:15], v[138:139]
	v_pk_mul_f32 v[142:143], v[2:3], v[142:143]
	v_pk_fma_f32 v[226:227], v[28:29], v[226:227], v[138:139]
	v_pk_fma_f32 v[228:229], v[16:17], v[228:229], v[142:143]
	v_add_f32_e32 v140, v226, v227
	v_add_f32_e32 v144, v228, v229
	s_nop 1
	v_permlane16_swap_b32_e32 v116, v120
	v_permlane16_swap_b32_e32 v124, v128
	v_permlane16_swap_b32_e32 v132, v136
	v_permlane16_swap_b32_e32 v140, v144
	v_add_f32_e32 v233, v116, v120
	v_add_f32_e32 v231, v124, v128
	v_add_f32_e32 v232, v132, v136
	v_add_f32_e32 v230, v140, v144
	s_nop 1
	v_permlane32_swap_b32_e32 v233, v231
	v_permlane32_swap_b32_e32 v232, v230
	v_pk_add_f32 v[230:231], v[232:233], v[230:231]
	v_pk_add_f32 v[230:231], v[230:231], 0 op_sel_hi:[1,0]
	v_ashrrev_i32_e32 v235, 31, v231
	v_ashrrev_i32_e32 v236, 31, v230
	v_or_b32_e32 v235, 0x80000000, v235
	v_or_b32_e32 v236, 0x80000000, v236
	v_xor_b32_e32 v235, v231, v235
	v_xor_b32_e32 v236, v230, v236
	v_cndmask_b32_e64 v235, 0, v235, s[90:91]
	v_cndmask_b32_e64 v236, 0, v236, s[92:93]
	ds_write_b32 v4, v235 offset:1024
	ds_write_b32 v237, v236
	s_sub_i32 s11, s9, 32
	s_cmp_ge_i32 s11, s6
	s_cbranch_scc1 .Lsc_exit
	s_cmp_lt_i32 s10, s6
	s_cbranch_scc1 .Lsc_w3n
	s_waitcnt vmcnt(0)
	s_branch .Lsc_m3

.Lsc_m3:
	v_mfma_f32_16x16x32_bf16 v[114:117], v[94:97], v[102:105], 0
	v_mfma_f32_16x16x32_bf16 v[118:121], v[82:85], v[102:105], 0
	v_mfma_f32_16x16x32_bf16 v[122:125], v[70:73], v[102:105], 0
	v_mfma_f32_16x16x32_bf16 v[126:129], v[58:61], v[102:105], 0
	v_mfma_f32_16x16x32_bf16 v[130:133], v[46:49], v[102:105], 0
	v_mfma_f32_16x16x32_bf16 v[134:137], v[34:37], v[102:105], 0
	v_mfma_f32_16x16x32_bf16 v[138:141], v[22:25], v[102:105], 0
	v_mfma_f32_16x16x32_bf16 v[142:145], v[10:13], v[102:105], 0
	v_mfma_f32_16x16x32_bf16 v[114:117], v[90:93], v[98:101], v[114:117]
	v_mfma_f32_16x16x32_bf16 v[118:121], v[78:81], v[98:101], v[118:121]
	v_mfma_f32_16x16x32_bf16 v[122:125], v[66:69], v[98:101], v[122:125]
	v_mfma_f32_16x16x32_bf16 v[126:129], v[54:57], v[98:101], v[126:129]
	v_mfma_f32_16x16x32_bf16 v[130:133], v[42:45], v[98:101], v[130:133]
	v_mfma_f32_16x16x32_bf16 v[134:137], v[30:33], v[98:101], v[134:137]
	v_mfma_f32_16x16x32_bf16 v[138:141], v[18:21], v[98:101], v[138:141]
	v_mfma_f32_16x16x32_bf16 v[142:145], v[6:9], v[98:101], v[142:145]
	s_cmp_lt_i32 s10, s6
	s_cbranch_scc0 .Lsc_np3
	s_add_i32 s11, s9, 0
	s_min_i32 s12, s11, s7
	s_ashr_i32 s13, s12, 31
	s_lshl_b64 s[12:13], s[12:13], 11
	v_lshl_add_u64 v[244:245], v[182:183], 0, s[12:13]
	global_load_dwordx4 v[102:105], v[244:245], off
	global_load_dwordx4 v[98:101], v[244:245], off offset:64
.Lsc_np3:
	v_cmp_le_i32_e64 s[90:91], v5, v0
	v_cmp_le_i32_e64 s[92:93], v5, v223
	v_add_u32_e32 v237, 0x10600, v4
	s_nop 1
	v_max_i32_e32 v226, 0, v115
	v_max_i32_e32 v228, 0, v119
	v_max_i32_e32 v227, 0, v116
	v_max_i32_e32 v229, 0, v120
	v_max_i32_e32 v115, 0, v117
	v_max_i32_e32 v119, 0, v121
	v_max_i32_e32 v114, 0, v114
	v_max_i32_e32 v118, 0, v118
	v_pk_mul_f32 v[114:115], v[86:87], v[114:115]
	v_pk_mul_f32 v[118:119], v[74:75], v[118:119]
	v_pk_fma_f32 v[226:227], v[184:185], v[226:227], v[114:115]
	v_pk_fma_f32 v[228:229], v[88:89], v[228:229], v[118:119]
	v_add_f32_e32 v116, v226, v227
	v_add_f32_e32 v120, v228, v229
	v_max_i32_e32 v226, 0, v123
	v_max_i32_e32 v228, 0, v127
	v_max_i32_e32 v227, 0, v124
	v_max_i32_e32 v229, 0, v128
	v_max_i32_e32 v123, 0, v125
	v_max_i32_e32 v127, 0, v129
	v_max_i32_e32 v122, 0, v122
	v_max_i32_e32 v126, 0, v126
	v_pk_mul_f32 v[122:123], v[62:63], v[122:123]
	v_pk_mul_f32 v[126:127], v[50:51], v[126:127]
	v_pk_fma_f32 v[226:227], v[76:77], v[226:227], v[122:123]
	v_pk_fma_f32 v[228:229], v[64:65], v[228:229], v[126:127]
	v_add_f32_e32 v124, v226, v227
	v_add_f32_e32 v128, v228, v229
	v_max_i32_e32 v226, 0, v131
	v_max_i32_e32 v228, 0, v135
	v_max_i32_e32 v227, 0, v132
	v_max_i32_e32 v229, 0, v136
	v_max_i32_e32 v131, 0, v133
	v_max_i32_e32 v135, 0, v137
	v_max_i32_e32 v130, 0, v130
	v_max_i32_e32 v134, 0, v134
	v_pk_mul_f32 v[130:131], v[38:39], v[130:131]
	v_pk_mul_f32 v[134:135], v[26:27], v[134:135]
	v_pk_fma_f32 v[226:227], v[52:53], v[226:227], v[130:131]
	v_pk_fma_f32 v[228:229], v[40:41], v[228:229], v[134:135]
	v_add_f32_e32 v132, v226, v227
	v_add_f32_e32 v136, v228, v229
	v_max_i32_e32 v226, 0, v139
	v_max_i32_e32 v228, 0, v143
	v_max_i32_e32 v227, 0, v140
	v_max_i32_e32 v229, 0, v144
	v_max_i32_e32 v139, 0, v141
	v_max_i32_e32 v143, 0, v145
	v_max_i32_e32 v138, 0, v138
	v_max_i32_e32 v142, 0, v142
	v_pk_mul_f32 v[138:139], v[14:15], v[138:139]
	v_pk_mul_f32 v[142:143], v[2:3], v[142:143]
	v_pk_fma_f32 v[226:227], v[28:29], v[226:227], v[138:139]
	v_pk_fma_f32 v[228:229], v[16:17], v[228:229], v[142:143]
	v_add_f32_e32 v140, v226, v227
	v_add_f32_e32 v144, v228, v229
	s_nop 1
	v_permlane16_swap_b32_e32 v116, v120
	v_permlane16_swap_b32_e32 v124, v128
	v_permlane16_swap_b32_e32 v132, v136
	v_permlane16_swap_b32_e32 v140, v144
	v_add_f32_e32 v233, v116, v120
	v_add_f32_e32 v231, v124, v128
	v_add_f32_e32 v232, v132, v136
	v_add_f32_e32 v230, v140, v144
	s_nop 1
	v_permlane32_swap_b32_e32 v233, v231
	v_permlane32_swap_b32_e32 v232, v230
	v_pk_add_f32 v[230:231], v[232:233], v[230:231]
	v_pk_add_f32 v[230:231], v[230:231], 0 op_sel_hi:[1,0]
	v_ashrrev_i32_e32 v235, 31, v231
	v_ashrrev_i32_e32 v236, 31, v230
	v_or_b32_e32 v235, 0x80000000, v235
	v_or_b32_e32 v236, 0x80000000, v236
	v_xor_b32_e32 v235, v231, v235
	v_xor_b32_e32 v236, v230, v236
	v_cndmask_b32_e64 v235, 0, v235, s[90:91]
	v_cndmask_b32_e64 v236, 0, v236, s[92:93]
	ds_write_b32 v4, v235 offset:1536
	ds_write_b32 v237, v236
	s_add_i32 s9, s9, 32
	v_add_u32_e32 v4, 0x800, v4
	v_add_u32_e32 v5, 0x200, v5
	v_lshl_add_u64 v[180:181], v[180:181], 0, s[34:35]
	s_cmp_ge_i32 s10, s6
	s_cbranch_scc0 .Lsc_step
.Lsc_exit:
	s_waitcnt vmcnt(0)
.LBB0_1639:
	s_add_i32 s53, s53, s22
	s_cmpk_gt_i32 s53, 0xfff
	s_cselect_b64 s[38:39], -1, 0
	s_cmpk_lt_i32 s53, 0x1000
	s_waitcnt lgkmcnt(0)
	s_barrier
	s_cbranch_scc0 .LBB0_1642
	s_and_b32 s6, s53, 0xf8
	s_lshl_b32 s9, s53, 12
	s_and_b32 s7, s53, 0x100
	s_and_b32 s9, s9, 0x7000
	s_xor_b32 s10, s6, 0xf8
	s_cmp_eq_u32 s7, 0
	s_cselect_b32 s6, s6, s10
	s_and_b32 s7, s53, 0xffffff00
	s_or_b32 s6, s6, s7
	s_add_i32 s6, s6, s9
	s_add_i32 s10, s6, s14
	s_ashr_i32 s11, s10, 31
	s_lshl_b64 s[10:11], s[10:11], 11
	v_lshl_add_u64 v[2:3], v[172:173], 0, s[10:11]
	s_add_i32 m0, s51, 0x22a00
	s_andn2_b64 vcc, exec, s[24:25]
	global_load_lds_dwordx4 v[2:3], off
	v_lshl_add_u64 v[2:3], v[2:3], 0, s[36:37]
	s_mov_b32 m0, s52
	s_nop 0
	global_load_lds_dwordx4 v[2:3], off
	s_cbranch_vccnz .LBB0_1642
	s_ashr_i32 s7, s6, 31
	s_lshl_b64 s[6:7], s[6:7], 6
	v_lshl_add_u64 v[2:3], v[166:167], 0, s[6:7]
	s_add_i32 m0, 0, 0x26a00
	s_nop 0
	global_load_lds_dwordx4 v[2:3], off

	.amdhsa_kernel _Z8fwd_mega6Params
		.amdhsa_group_segment_fixed_size 0
		.amdhsa_private_segment_fixed_size 0
		.amdhsa_kernarg_size 536
		.amdhsa_user_sgpr_count 2
		.amdhsa_user_sgpr_dispatch_ptr 0
		.amdhsa_user_sgpr_queue_ptr 0
		.amdhsa_user_sgpr_kernarg_segment_ptr 1
		.amdhsa_user_sgpr_dispatch_id 0
		.amdhsa_user_sgpr_kernarg_preload_length 0
		.amdhsa_user_sgpr_kernarg_preload_offset 0
		.amdhsa_user_sgpr_private_segment_size 0
		.amdhsa_uses_dynamic_stack 0
		.amdhsa_enable_private_segment 0
		.amdhsa_system_sgpr_workgroup_id_x 1
		.amdhsa_system_sgpr_workgroup_id_y 0
		.amdhsa_system_sgpr_workgroup_id_z 0
		.amdhsa_system_sgpr_workgroup_info 0
		.amdhsa_system_vgpr_workitem_id 2
		.amdhsa_next_free_vgpr 256
		.amdhsa_next_free_sgpr 102
		.amdhsa_accum_offset 256
		.amdhsa_reserve_vcc 1
		.amdhsa_float_round_mode_32 0
		.amdhsa_float_round_mode_16_64 0
		.amdhsa_float_denorm_mode_32 3
		.amdhsa_float_denorm_mode_16_64 3
		.amdhsa_dx10_clamp 1
		.amdhsa_ieee_mode 1
		.amdhsa_fp16_overflow 0
		.amdhsa_tg_split 0
		.amdhsa_exception_fp_ieee_invalid_op 0
		.amdhsa_exception_fp_denorm_src 0
		.amdhsa_exception_fp_ieee_div_zero 0
		.amdhsa_exception_fp_ieee_overflow 0
		.amdhsa_exception_fp_ieee_underflow 0
		.amdhsa_exception_fp_ieee_inexact 0
		.amdhsa_exception_int_div_zero 0
	.end_amdhsa_kernel

amdhsa.kernels:
  - .agpr_count:     0
    .args:
      - .offset:         0
        .size:           280
        .value_kind:     by_value
      - .offset:         280
        .size:           4
        .value_kind:     hidden_block_count_x
      - .offset:         284
        .size:           4
        .value_kind:     hidden_block_count_y
      - .offset:         288
        .size:           4
        .value_kind:     hidden_block_count_z
      - .offset:         292
        .size:           2
        .value_kind:     hidden_group_size_x
      - .offset:         294
        .size:           2
        .value_kind:     hidden_group_size_y
      - .offset:         296
        .size:           2
        .value_kind:     hidden_group_size_z
      - .offset:         298
        .size:           2
        .value_kind:     hidden_remainder_x
      - .offset:         300
        .size:           2
        .value_kind:     hidden_remainder_y
      - .offset:         302
        .size:           2
        .value_kind:     hidden_remainder_z
      - .offset:         320
        .size:           8
        .value_kind:     hidden_global_offset_x
      - .offset:         328
        .size:           8
        .value_kind:     hidden_global_offset_y
      - .offset:         336
        .size:           8
        .value_kind:     hidden_global_offset_z
      - .offset:         344
        .size:           2
        .value_kind:     hidden_grid_dims
      - .offset:         368
        .size:           8
        .value_kind:     hidden_multigrid_sync_arg
      - .offset:         400
        .size:           4
        .value_kind:     hidden_dynamic_lds_size
    .group_segment_fixed_size: 0
    .kernarg_segment_align: 8
    .kernarg_segment_size: 536
    .language:       OpenCL C
    .language_version:
      - 2
      - 0
    .max_flat_workgroup_size: 512
    .name:           _Z8fwd_mega6Params
    .private_segment_fixed_size: 0
    .sgpr_count:     108
    .sgpr_spill_count: 0
    .symbol:         _Z8fwd_mega6Params.kd
    .uniform_work_group_size: 1
    .uses_dynamic_stack: false
    .vgpr_count:     256
    .vgpr_spill_count: 0
    .wavefront_size: 64
